# PV fragment reads two pairs ahead (three fragment buffers)
# baseline (speedup 1.0000x reference)
.LBB0_299:
	v_sub_f32_e32 v63, v63, v124
	v_sub_f32_e32 v62, v62, v124
	v_sub_f32_e32 v61, v61, v124
	v_sub_f32_e32 v60, v60, v124
	v_sub_f32_e32 v59, v59, v124
	v_sub_f32_e32 v58, v58, v124
	v_sub_f32_e32 v57, v57, v124
	v_sub_f32_e32 v56, v56, v124
	v_sub_f32_e32 v55, v55, v124
	v_sub_f32_e32 v54, v54, v124
	v_sub_f32_e32 v53, v53, v124
	v_sub_f32_e32 v52, v52, v124
	v_sub_f32_e32 v51, v51, v124
	v_sub_f32_e32 v50, v50, v124
	v_sub_f32_e32 v49, v49, v124
	v_sub_f32_e32 v48, v48, v124
	v_sub_f32_e32 v126, v47, v124
	v_sub_f32_e32 v127, v46, v124
	v_sub_f32_e32 v128, v45, v124
	v_sub_f32_e32 v129, v44, v124
	v_sub_f32_e32 v130, v43, v124
	v_sub_f32_e32 v131, v42, v124
	v_sub_f32_e32 v132, v41, v124
	v_sub_f32_e32 v133, v40, v124
	v_sub_f32_e32 v47, v39, v124
	v_sub_f32_e32 v39, v38, v124
	v_sub_f32_e32 v38, v37, v124
	v_sub_f32_e32 v37, v36, v124
	v_sub_f32_e32 v36, v35, v124
	v_sub_f32_e32 v35, v34, v124
	v_sub_f32_e32 v34, v33, v124
	v_sub_f32_e32 v33, v32, v124
	v_exp_f32_e32 v32, v48
	v_exp_f32_e32 v40, v33
	v_exp_f32_e32 v33, v49
	v_exp_f32_e32 v41, v34
	v_exp_f32_e32 v34, v50
	v_exp_f32_e32 v42, v35
	v_exp_f32_e32 v35, v51
	v_exp_f32_e32 v43, v36
	v_exp_f32_e32 v36, v52
	v_exp_f32_e32 v44, v37
	v_exp_f32_e32 v37, v53
	v_exp_f32_e32 v45, v38
	v_exp_f32_e32 v38, v54
	v_exp_f32_e32 v46, v39
	v_exp_f32_e32 v39, v55
	v_exp_f32_e32 v47, v47
	v_exp_f32_e32 v48, v56
	v_exp_f32_e32 v50, v133
	v_exp_f32_e32 v49, v57
	v_exp_f32_e32 v51, v132
	v_exp_f32_e32 v52, v58
	v_exp_f32_e32 v54, v131
	v_exp_f32_e32 v53, v59
	v_exp_f32_e32 v55, v130
	v_exp_f32_e32 v56, v60
	v_exp_f32_e32 v58, v129
	v_exp_f32_e32 v57, v61
	v_exp_f32_e32 v60, v62
	v_exp_f32_e32 v62, v127
	v_exp_f32_e32 v61, v63
	v_exp_f32_e32 v63, v126
	v_exp_f32_e32 v59, v128
	v_pk_add_f32 v[126:127], v[52:53], v[54:55]
	v_pk_add_f32 v[128:129], v[34:35], v[42:43]
	v_pk_add_f32 v[130:131], v[60:61], v[62:63]
	v_pk_add_f32 v[132:133], v[38:39], v[46:47]
	v_pk_add_f32 v[134:135], v[48:49], v[50:51]
	v_pk_add_f32 v[136:137], v[32:33], v[40:41]
	v_pk_add_f32 v[138:139], v[56:57], v[58:59]
	v_pk_add_f32 v[140:141], v[36:37], v[44:45]
	v_pk_add_f32 v[134:135], v[136:137], v[134:135]
	v_pk_add_f32 v[138:139], v[140:141], v[138:139]
	v_pk_add_f32 v[130:131], v[132:133], v[130:131]
	v_pk_add_f32 v[126:127], v[128:129], v[126:127]
	v_pk_add_f32 v[128:129], v[134:135], v[138:139]
	v_pk_add_f32 v[126:127], v[126:127], v[130:131]
	v_add_f32_e32 v128, v128, v129
	v_add_f32_e32 v126, v126, v127
	v_add_f32_e32 v126, v128, v126
	v_add_u32_e32 v125, s61, v116
	v_fmac_f32_e32 v126, v122, v123
	v_cvt_pk_bf16_f32 v32, v32, v33
	v_cvt_pk_bf16_f32 v33, v34, v35
	v_cvt_pk_bf16_f32 v34, v36, v37
	v_cvt_pk_bf16_f32 v35, v38, v39
	v_cvt_pk_bf16_f32 v36, v48, v49
	v_cvt_pk_bf16_f32 v37, v52, v53
	v_cvt_pk_bf16_f32 v38, v56, v57
	v_cvt_pk_bf16_f32 v39, v60, v61
	v_cvt_pk_bf16_f32 v40, v40, v41
	v_cvt_pk_bf16_f32 v41, v42, v43
	v_cvt_pk_bf16_f32 v42, v44, v45
	v_cvt_pk_bf16_f32 v43, v46, v47
	v_cvt_pk_bf16_f32 v44, v50, v51
	v_cvt_pk_bf16_f32 v45, v54, v55
	v_cvt_pk_bf16_f32 v46, v58, v59
	v_cvt_pk_bf16_f32 v47, v62, v63
	s_setprio 1
	v_add3_u32 v52, v125, v112, v117
	ds_read_b64_tr_b16 v[216:217], v52 offset:8192
	ds_read_b64_tr_b16 v[218:219], v52 offset:8704
	ds_read_b64_tr_b16 v[220:221], v52 offset:9216
	ds_read_b64_tr_b16 v[222:223], v52 offset:9728
	ds_read_b64_tr_b16 v[224:225], v52 offset:10240
	ds_read_b64_tr_b16 v[226:227], v52 offset:10752
	s_waitcnt lgkmcnt(4)
	v_mfma_f32_32x32x16_bf16 v[0:15], v[32:35], v[216:219], v[0:15]
	ds_read_b64_tr_b16 v[216:217], v52 offset:11264
	ds_read_b64_tr_b16 v[218:219], v52 offset:11776
	s_waitcnt lgkmcnt(4)
	v_mfma_f32_32x32x16_bf16 v[0:15], v[36:39], v[220:223], v[0:15]
	ds_read_b64_tr_b16 v[220:221], v52 offset:12288
	ds_read_b64_tr_b16 v[222:223], v52 offset:12800
	s_waitcnt lgkmcnt(4)
	v_mfma_f32_32x32x16_bf16 v[0:15], v[40:43], v[224:227], v[0:15]
	ds_read_b64_tr_b16 v[224:225], v52 offset:13312
	ds_read_b64_tr_b16 v[226:227], v52 offset:13824
	s_waitcnt lgkmcnt(4)
	v_mfma_f32_32x32x16_bf16 v[0:15], v[44:47], v[216:219], v[0:15]
	ds_read_b64_tr_b16 v[216:217], v52 offset:14336
	ds_read_b64_tr_b16 v[218:219], v52 offset:14848
	s_waitcnt lgkmcnt(4)
	v_mfma_f32_32x32x16_bf16 v[16:31], v[32:35], v[220:223], v[16:31]
	ds_read_b64_tr_b16 v[220:221], v52 offset:15360
	ds_read_b64_tr_b16 v[222:223], v52 offset:15872
	s_waitcnt lgkmcnt(4)
	v_mfma_f32_32x32x16_bf16 v[16:31], v[36:39], v[224:227], v[16:31]
	s_waitcnt lgkmcnt(2)
	v_mfma_f32_32x32x16_bf16 v[16:31], v[40:43], v[216:219], v[16:31]
	s_waitcnt lgkmcnt(0)
	v_mfma_f32_32x32x16_bf16 v[16:31], v[44:47], v[220:223], v[16:31]
	s_setprio 0
	s_mov_b32 s61, 0
	v_mov_b32_e32 v122, v126
	v_mov_b32_e32 v123, v124

.LBB0_3848:
	s_or_b64 exec, exec, s[12:13]
	v_cvt_pk_bf16_f32 v50, v144, v146
	s_waitcnt lgkmcnt(14)
	v_cvt_pk_bf16_f32 v51, v148, v151
	v_cvt_pk_bf16_f32 v52, v153, v155
	v_cvt_pk_bf16_f32 v53, v157, v159
	v_cvt_pk_bf16_f32 v54, v163, v165
	s_waitcnt lgkmcnt(13)
	v_cvt_pk_bf16_f32 v55, v167, v187
	v_cvt_pk_bf16_f32 v56, v189, v191
	s_waitcnt lgkmcnt(12)
	v_cvt_pk_bf16_f32 v57, v193, v195
	s_waitcnt lgkmcnt(11)
	v_cvt_pk_bf16_f32 v60, v145, v147
	v_cvt_pk_bf16_f32 v61, v150, v152
	s_waitcnt lgkmcnt(10)
	v_cvt_pk_bf16_f32 v62, v154, v156
	v_cvt_pk_bf16_f32 v63, v158, v162
	s_waitcnt lgkmcnt(9)
	v_cvt_pk_bf16_f32 v64, v164, v166
	v_cvt_pk_bf16_f32 v65, v186, v188
	s_waitcnt lgkmcnt(8)
	v_cvt_pk_bf16_f32 v66, v190, v192
	s_waitcnt lgkmcnt(6)
	v_cvt_pk_bf16_f32 v67, v194, v196
	v_add_u32_e32 v59, s20, v181
	s_setprio 1
	s_waitcnt lgkmcnt(0)
	ds_read_b64_tr_b16 v[216:217], v59 offset:8192
	ds_read_b64_tr_b16 v[218:219], v59 offset:8704
	ds_read_b64_tr_b16 v[220:221], v59 offset:9216
	ds_read_b64_tr_b16 v[222:223], v59 offset:9728
	ds_read_b64_tr_b16 v[224:225], v59 offset:10240
	ds_read_b64_tr_b16 v[226:227], v59 offset:10752
	s_waitcnt lgkmcnt(4)
	v_mfma_f32_32x32x16_bf16 v[2:17], v[50:53], v[216:219], v[2:17]
	ds_read_b64_tr_b16 v[216:217], v59 offset:11264
	ds_read_b64_tr_b16 v[218:219], v59 offset:11776
	s_waitcnt lgkmcnt(4)
	v_mfma_f32_32x32x16_bf16 v[2:17], v[54:57], v[220:223], v[2:17]
	ds_read_b64_tr_b16 v[220:221], v59 offset:12288
	ds_read_b64_tr_b16 v[222:223], v59 offset:12800
	s_waitcnt lgkmcnt(4)
	v_mfma_f32_32x32x16_bf16 v[2:17], v[60:63], v[224:227], v[2:17]
	ds_read_b64_tr_b16 v[224:225], v59 offset:13312
	ds_read_b64_tr_b16 v[226:227], v59 offset:13824
	s_waitcnt lgkmcnt(4)
	v_mfma_f32_32x32x16_bf16 v[2:17], v[64:67], v[216:219], v[2:17]
	ds_read_b64_tr_b16 v[216:217], v59 offset:14336
	ds_read_b64_tr_b16 v[218:219], v59 offset:14848
	s_waitcnt lgkmcnt(4)
	v_mfma_f32_32x32x16_bf16 v[18:33], v[50:53], v[220:223], v[18:33]
	ds_read_b64_tr_b16 v[220:221], v59 offset:15360
	ds_read_b64_tr_b16 v[222:223], v59 offset:15872
	s_waitcnt lgkmcnt(4)
	v_mfma_f32_32x32x16_bf16 v[18:33], v[54:57], v[224:227], v[18:33]
	s_waitcnt lgkmcnt(2)
	v_mfma_f32_32x32x16_bf16 v[18:33], v[60:63], v[216:219], v[18:33]
	s_waitcnt lgkmcnt(0)
	v_mfma_f32_32x32x16_bf16 v[18:33], v[64:67], v[220:223], v[18:33]
	s_setprio 0
	s_add_i32 s19, s19, 1
	s_cmp_lt_u32 s19, s15
	s_mov_b64 s[12:13], -1
	s_cbranch_scc1 .LBB0_3850
	s_add_i32 s20, s16, 0x4000
	s_mov_b64 s[12:13], 0

.LBB0_4173:
	v_sub_f32_e32 v108, v65, v1
	v_sub_f32_e32 v109, v64, v1
	v_sub_f32_e32 v110, v63, v1
	v_sub_f32_e32 v111, v62, v1
	v_sub_f32_e32 v61, v61, v1
	v_sub_f32_e32 v60, v60, v1
	v_sub_f32_e32 v59, v59, v1
	v_sub_f32_e32 v58, v58, v1
	v_sub_f32_e32 v57, v57, v1
	v_sub_f32_e32 v56, v56, v1
	v_sub_f32_e32 v55, v55, v1
	v_sub_f32_e32 v54, v54, v1
	v_sub_f32_e32 v53, v53, v1
	v_sub_f32_e32 v52, v52, v1
	v_sub_f32_e32 v51, v51, v1
	v_sub_f32_e32 v50, v50, v1
	v_sub_f32_e32 v112, v49, v1
	v_sub_f32_e32 v113, v48, v1
	v_sub_f32_e32 v114, v47, v1
	v_sub_f32_e32 v115, v46, v1
	v_sub_f32_e32 v116, v45, v1
	v_sub_f32_e32 v117, v44, v1
	v_sub_f32_e32 v65, v43, v1
	v_sub_f32_e32 v63, v42, v1
	v_sub_f32_e32 v45, v41, v1
	v_sub_f32_e32 v43, v40, v1
	v_sub_f32_e32 v41, v39, v1
	v_sub_f32_e32 v39, v38, v1
	v_sub_f32_e32 v38, v37, v1
	v_sub_f32_e32 v40, v36, v1
	v_sub_f32_e32 v37, v35, v1
	v_sub_f32_e32 v35, v34, v1
	v_exp_f32_e32 v34, v50
	v_exp_f32_e32 v36, v35
	v_exp_f32_e32 v35, v51
	v_exp_f32_e32 v37, v37
	v_exp_f32_e32 v46, v52
	v_exp_f32_e32 v48, v40
	v_exp_f32_e32 v47, v53
	v_exp_f32_e32 v49, v38
	v_exp_f32_e32 v38, v54
	v_exp_f32_e32 v40, v39
	v_exp_f32_e32 v39, v55
	v_exp_f32_e32 v41, v41
	v_exp_f32_e32 v42, v56
	v_exp_f32_e32 v44, v43
	v_exp_f32_e32 v43, v57
	v_exp_f32_e32 v45, v45
	v_exp_f32_e32 v62, v58
	v_exp_f32_e32 v64, v63
	v_exp_f32_e32 v63, v59
	v_exp_f32_e32 v65, v65
	v_exp_f32_e32 v58, v60
	v_exp_f32_e32 v60, v117
	v_exp_f32_e32 v59, v61
	v_exp_f32_e32 v61, v116
	v_exp_f32_e32 v50, v111
	v_exp_f32_e32 v52, v115
	v_exp_f32_e32 v51, v110
	v_exp_f32_e32 v53, v114
	v_exp_f32_e32 v54, v109
	v_exp_f32_e32 v56, v113
	v_exp_f32_e32 v55, v108
	v_exp_f32_e32 v57, v112
	v_cvt_pk_bf16_f32 v108, v34, v35
	v_cvt_pk_bf16_f32 v109, v46, v47
	v_cvt_pk_bf16_f32 v110, v38, v39
	v_cvt_pk_bf16_f32 v111, v42, v43
	v_cvt_pk_bf16_f32 v112, v62, v63
	v_cvt_pk_bf16_f32 v113, v58, v59
	v_cvt_pk_bf16_f32 v114, v50, v51
	v_cvt_pk_bf16_f32 v115, v54, v55
	v_cvt_pk_bf16_f32 v116, v36, v37
	v_cvt_pk_bf16_f32 v117, v48, v49
	v_cvt_pk_bf16_f32 v118, v40, v41
	v_cvt_pk_bf16_f32 v119, v44, v45
	v_cvt_pk_bf16_f32 v120, v64, v65
	v_cvt_pk_bf16_f32 v121, v60, v61
	v_cvt_pk_bf16_f32 v122, v52, v53
	v_cvt_pk_bf16_f32 v123, v56, v57
	s_setprio 1
	v_add_u32_e32 v124, s17, v181
	ds_read_b64_tr_b16 v[216:217], v124 offset:8192
	ds_read_b64_tr_b16 v[218:219], v124 offset:8704
	ds_read_b64_tr_b16 v[220:221], v124 offset:9216
	ds_read_b64_tr_b16 v[222:223], v124 offset:9728
	ds_read_b64_tr_b16 v[224:225], v124 offset:10240
	ds_read_b64_tr_b16 v[226:227], v124 offset:10752
	s_waitcnt lgkmcnt(4)
	v_mfma_f32_32x32x16_bf16 v[2:17], v[108:111], v[216:219], v[2:17]
	ds_read_b64_tr_b16 v[216:217], v124 offset:11264
	ds_read_b64_tr_b16 v[218:219], v124 offset:11776
	s_waitcnt lgkmcnt(4)
	v_mfma_f32_32x32x16_bf16 v[2:17], v[112:115], v[220:223], v[2:17]
	ds_read_b64_tr_b16 v[220:221], v124 offset:12288
	ds_read_b64_tr_b16 v[222:223], v124 offset:12800
	s_waitcnt lgkmcnt(4)
	v_mfma_f32_32x32x16_bf16 v[2:17], v[116:119], v[224:227], v[2:17]
	ds_read_b64_tr_b16 v[224:225], v124 offset:13312
	ds_read_b64_tr_b16 v[226:227], v124 offset:13824
	s_waitcnt lgkmcnt(4)
	v_mfma_f32_32x32x16_bf16 v[2:17], v[120:123], v[216:219], v[2:17]
	ds_read_b64_tr_b16 v[216:217], v124 offset:14336
	ds_read_b64_tr_b16 v[218:219], v124 offset:14848
	s_waitcnt lgkmcnt(4)
	v_mfma_f32_32x32x16_bf16 v[18:33], v[108:111], v[220:223], v[18:33]
	ds_read_b64_tr_b16 v[220:221], v124 offset:15360
	ds_read_b64_tr_b16 v[222:223], v124 offset:15872
	s_waitcnt lgkmcnt(4)
	v_mfma_f32_32x32x16_bf16 v[18:33], v[112:115], v[224:227], v[18:33]
	s_waitcnt lgkmcnt(2)
	v_mfma_f32_32x32x16_bf16 v[18:33], v[116:119], v[216:219], v[18:33]
	s_waitcnt lgkmcnt(0)
	v_mfma_f32_32x32x16_bf16 v[18:33], v[120:123], v[220:223], v[18:33]
	s_setprio 0
	s_cmp_ge_u32 s13, s48
	s_cselect_b64 s[10:11], -1, 0
	s_and_b64 vcc, exec, s[10:11]
	s_cbranch_vccnz .LBB0_4175
	s_xor_b32 s16, s16, 0x4000
	v_add_u32_e32 v108, s16, v182
	ds_write_b128 v108, v[74:77]
	ds_write_b128 v108, v[78:81] offset:8192
